# ring loops: running-sum update as one v_fma (was v_fmac + v_mov), selection-mask compare moved ahead so the hazard s_nop is no longer needed
# baseline (speedup 1.0000x reference)
.LBB0_1158:
	v_max_f32_e32 v108, v34, v35
	v_max3_f32 v108, v108, v36, v37
	v_max3_f32 v108, v108, v38, v39
	v_max3_f32 v108, v108, v40, v41
	v_max3_f32 v108, v108, v42, v43
	v_max3_f32 v108, v108, v44, v45
	v_max3_f32 v108, v108, v46, v47
	v_max3_f32 v108, v108, v48, v49
	v_max3_f32 v108, v108, v50, v51
	v_max3_f32 v108, v108, v52, v53
	v_max3_f32 v108, v108, v54, v55
	v_max3_f32 v108, v108, v56, v57
	v_max3_f32 v108, v108, v58, v59
	v_max3_f32 v108, v108, v60, v61
	v_max3_f32 v108, v108, v62, v63
	v_max3_f32 v108, v108, v64, v65
	ds_bpermute_b32 v110, v209, v108
	v_sub_co_u32_e64 v111, vcc, s42, 32
	v_lshrrev_b32_e32 v0, s42, v102
	v_lshrrev_b32_e32 v111, v111, v103
	v_cndmask_b32_e32 v0, v111, v0, vcc
	v_and_b32_e32 v0, 1, v0
	v_cmp_eq_u32_e64 s[2:3], 0, v0
	s_waitcnt lgkmcnt(0)
	v_max_f32_e32 v108, v108, v110
	v_cndmask_b32_e64 v0, v108, v196, s[2:3]
	v_max_f32_e32 v117, v116, v0
	v_sub_f32_e32 v0, v116, v117
	v_exp_f32_e32 v108, v0
	s_nop 0
	v_cmp_neq_f32_e32 vcc, 1.0, v108
	s_cbranch_vccz .LBB0_1160
	v_pk_mul_f32 v[32:33], v[32:33], v[108:109] op_sel_hi:[1,0]
	v_pk_mul_f32 v[30:31], v[30:31], v[108:109] op_sel_hi:[1,0]
	v_pk_mul_f32 v[28:29], v[28:29], v[108:109] op_sel_hi:[1,0]
	v_pk_mul_f32 v[26:27], v[26:27], v[108:109] op_sel_hi:[1,0]
	v_pk_mul_f32 v[24:25], v[24:25], v[108:109] op_sel_hi:[1,0]
	v_pk_mul_f32 v[22:23], v[22:23], v[108:109] op_sel_hi:[1,0]
	v_pk_mul_f32 v[20:21], v[20:21], v[108:109] op_sel_hi:[1,0]
	v_pk_mul_f32 v[18:19], v[18:19], v[108:109] op_sel_hi:[1,0]
	v_pk_mul_f32 v[16:17], v[16:17], v[108:109] op_sel_hi:[1,0]
	v_pk_mul_f32 v[14:15], v[14:15], v[108:109] op_sel_hi:[1,0]
	v_pk_mul_f32 v[12:13], v[12:13], v[108:109] op_sel_hi:[1,0]
	v_pk_mul_f32 v[10:11], v[10:11], v[108:109] op_sel_hi:[1,0]
	v_pk_mul_f32 v[8:9], v[8:9], v[108:109] op_sel_hi:[1,0]
	v_pk_mul_f32 v[6:7], v[6:7], v[108:109] op_sel_hi:[1,0]
	v_pk_mul_f32 v[4:5], v[4:5], v[108:109] op_sel_hi:[1,0]
	v_pk_mul_f32 v[2:3], v[2:3], v[108:109] op_sel_hi:[1,0]
.LBB0_1160:
	v_max_f32_e32 v0, 0xefa18f08, v117
	v_cndmask_b32_e64 v116, v0, v198, s[2:3]
	v_sub_f32_e32 v0, v34, v116
	v_exp_f32_e32 v34, v0
	v_sub_f32_e32 v0, v50, v116
	v_exp_f32_e32 v50, v0
	v_sub_f32_e32 v0, v35, v116
	v_exp_f32_e32 v154, v0
	v_sub_f32_e32 v0, v51, v116
	v_exp_f32_e32 v0, v0
	v_sub_f32_e32 v35, v36, v116
	v_add_f32_e32 v155, v34, v50
	v_exp_f32_e32 v36, v35
	v_sub_f32_e32 v35, v52, v116
	v_pk_add_f32 v[110:111], v[154:155], v[0:1]
	v_exp_f32_e32 v52, v35
	v_sub_f32_e32 v35, v37, v116
	v_pk_add_f32 v[110:111], v[110:111], v[110:111] op_sel_hi:[0,1]
	v_exp_f32_e32 v156, v35
	v_sub_f32_e32 v35, v53, v116
	v_exp_f32_e32 v110, v35
	v_sub_f32_e32 v37, v38, v116
	v_add_f32_e32 v157, v36, v52
	v_exp_f32_e32 v38, v37
	v_sub_f32_e32 v37, v54, v116
	v_pk_add_f32 v[118:119], v[156:157], v[110:111]
	v_exp_f32_e32 v54, v37
	v_sub_f32_e32 v37, v39, v116
	v_pk_add_f32 v[158:159], v[118:119], v[118:119] op_sel_hi:[0,1]
	v_exp_f32_e32 v160, v37
	v_sub_f32_e32 v37, v55, v116
	v_exp_f32_e32 v158, v37
	v_sub_f32_e32 v37, v40, v116
	v_add_f32_e32 v161, v38, v54
	v_exp_f32_e32 v40, v37
	v_sub_f32_e32 v37, v56, v116
	v_pk_add_f32 v[126:127], v[160:161], v[158:159]
	v_exp_f32_e32 v56, v37
	v_sub_f32_e32 v37, v41, v116
	v_pk_add_f32 v[186:187], v[126:127], v[126:127] op_sel_hi:[0,1]
	v_exp_f32_e32 v188, v37
	v_sub_f32_e32 v37, v57, v116
	v_exp_f32_e32 v186, v37
	v_sub_f32_e32 v37, v42, v116
	v_add_f32_e32 v189, v40, v56
	v_exp_f32_e32 v42, v37
	v_sub_f32_e32 v37, v58, v116
	v_pk_add_f32 v[134:135], v[188:189], v[186:187]
	v_exp_f32_e32 v58, v37
	v_sub_f32_e32 v37, v43, v116
	v_pk_add_f32 v[190:191], v[134:135], v[134:135] op_sel_hi:[0,1]
	v_exp_f32_e32 v192, v37
	v_sub_f32_e32 v37, v59, v116
	v_exp_f32_e32 v190, v37
	v_sub_f32_e32 v37, v44, v116
	v_add_f32_e32 v193, v42, v58
	v_exp_f32_e32 v44, v37
	v_sub_f32_e32 v37, v60, v116
	v_pk_add_f32 v[142:143], v[192:193], v[190:191]
	v_exp_f32_e32 v60, v37
	v_sub_f32_e32 v37, v45, v116
	v_pk_add_f32 v[194:195], v[142:143], v[142:143] op_sel_hi:[0,1]
	v_exp_f32_e32 v224, v37
	v_sub_f32_e32 v37, v61, v116
	v_exp_f32_e32 v194, v37
	v_lshl_add_u32 v35, s45, 14, v112
	ds_read_b64_tr_b16 v[118:119], v35 offset:8192
	ds_read_b64_tr_b16 v[120:121], v35 offset:8704
	ds_read_b64_tr_b16 v[122:123], v35 offset:9216
	ds_read_b64_tr_b16 v[124:125], v35 offset:9728
	ds_read_b64_tr_b16 v[126:127], v35 offset:12288
	ds_read_b64_tr_b16 v[128:129], v35 offset:12800
	ds_read_b64_tr_b16 v[130:131], v35 offset:13312
	ds_read_b64_tr_b16 v[132:133], v35 offset:13824
	ds_read_b64_tr_b16 v[134:135], v35 offset:10240
	ds_read_b64_tr_b16 v[136:137], v35 offset:10752
	ds_read_b64_tr_b16 v[138:139], v35 offset:11264
	ds_read_b64_tr_b16 v[140:141], v35 offset:11776
	ds_read_b64_tr_b16 v[142:143], v35 offset:14336
	ds_read_b64_tr_b16 v[144:145], v35 offset:14848
	ds_read_b64_tr_b16 v[146:147], v35 offset:15360
	ds_read_b64_tr_b16 v[148:149], v35 offset:15872
	v_add_f32_e32 v225, v44, v60
	v_sub_f32_e32 v35, v46, v116
	v_pk_add_f32 v[150:151], v[224:225], v[194:195]
	v_exp_f32_e32 v46, v35
	v_sub_f32_e32 v35, v62, v116
	v_pk_add_f32 v[226:227], v[150:151], v[150:151] op_sel_hi:[0,1]
	v_cvt_pk_bf16_f32 v150, v34, v154
	v_cvt_pk_bf16_f32 v151, v36, v156
	v_cvt_pk_bf16_f32 v152, v38, v160
	v_cvt_pk_bf16_f32 v153, v40, v188
	v_exp_f32_e32 v62, v35
	v_sub_f32_e32 v35, v47, v116
	s_waitcnt lgkmcnt(0)
	v_mfma_f32_32x32x16_bf16 v[2:17], v[118:121], v[150:153], v[2:17]
	v_exp_f32_e32 v228, v35
	v_sub_f32_e32 v35, v63, v116
	v_exp_f32_e32 v226, v35
	v_sub_f32_e32 v35, v48, v116
	v_exp_f32_e32 v48, v35
	v_sub_f32_e32 v35, v49, v116
	v_exp_f32_e32 v49, v35
	v_mfma_f32_32x32x16_bf16 v[18:33], v[126:129], v[150:153], v[18:33]
	v_cvt_pk_bf16_f32 v118, v42, v192
	v_cvt_pk_bf16_f32 v119, v44, v224
	v_cvt_pk_bf16_f32 v120, v46, v228
	v_cvt_pk_bf16_f32 v121, v48, v49
	v_sub_f32_e32 v35, v64, v116
	v_exp_f32_e32 v64, v35
	v_sub_f32_e32 v35, v65, v116
	v_mfma_f32_32x32x16_bf16 v[2:17], v[122:125], v[118:121], v[2:17]
	v_exp_f32_e32 v65, v35
	v_add_f32_e32 v229, v46, v62
	v_pk_add_f32 v[122:123], v[228:229], v[226:227]
	v_add_f32_e32 v111, v48, v64
	v_pk_add_f32 v[122:123], v[122:123], v[122:123] op_sel_hi:[0,1]
	v_mov_b32_e32 v122, v65
	v_mfma_f32_32x32x16_bf16 v[18:33], v[130:133], v[118:121], v[18:33]
	v_cvt_pk_bf16_f32 v118, v50, v0
	v_cvt_pk_bf16_f32 v119, v52, v110
	v_cvt_pk_bf16_f32 v120, v54, v158
	v_cvt_pk_bf16_f32 v121, v56, v186
	v_mov_b32_e32 v110, v49
	v_pk_add_f32 v[110:111], v[110:111], v[122:123]
	v_mfma_f32_32x32x16_bf16 v[2:17], v[134:137], v[118:121], v[2:17]
	v_add_f32_e32 v0, v110, v111
	v_fma_f32 v115, v115, v108, v0
	v_mfma_f32_32x32x16_bf16 v[18:33], v[142:145], v[118:121], v[18:33]
	v_cvt_pk_bf16_f32 v118, v58, v190
	v_cvt_pk_bf16_f32 v119, v60, v194
	v_cvt_pk_bf16_f32 v120, v62, v226
	v_cvt_pk_bf16_f32 v121, v64, v65
	s_nop 1
	v_mfma_f32_32x32x16_bf16 v[2:17], v[138:141], v[118:121], v[2:17]
	v_mfma_f32_32x32x16_bf16 v[18:33], v[146:149], v[118:121], v[18:33]
	s_branch .LBB0_1162

.LBB0_1171:
	v_max_f32_e32 v108, v66, v67
	v_max3_f32 v108, v108, v68, v69
	v_max3_f32 v108, v108, v70, v71
	v_max3_f32 v108, v108, v72, v73
	v_max3_f32 v108, v108, v74, v75
	v_max3_f32 v108, v108, v76, v77
	v_max3_f32 v108, v108, v78, v79
	v_max3_f32 v108, v108, v80, v81
	v_max3_f32 v108, v108, v82, v83
	v_max3_f32 v108, v108, v84, v85
	v_max3_f32 v108, v108, v86, v87
	v_max3_f32 v108, v108, v88, v89
	v_max3_f32 v108, v108, v90, v91
	v_max3_f32 v108, v108, v92, v93
	v_max3_f32 v108, v108, v94, v95
	v_max3_f32 v108, v108, v96, v97
	ds_bpermute_b32 v110, v209, v108
	s_cmp_lt_u32 s42, 32
	s_cselect_b64 vcc, -1, 0
	s_sub_i32 s2, s42, 31
	v_lshrrev_b32_e32 v0, s40, v102
	v_lshrrev_b32_e32 v111, s2, v103
	v_cndmask_b32_e32 v0, v111, v0, vcc
	v_and_b32_e32 v0, 1, v0
	v_cmp_eq_u32_e64 s[2:3], 0, v0
	s_waitcnt lgkmcnt(0)
	v_max_f32_e32 v108, v108, v110
	v_cndmask_b32_e64 v0, v108, v196, s[2:3]
	v_max_f32_e32 v116, v117, v0
	v_sub_f32_e32 v0, v117, v116
	v_exp_f32_e32 v108, v0
	s_nop 0
	v_cmp_neq_f32_e32 vcc, 1.0, v108
	s_cbranch_vccz .LBB0_1173
	v_pk_mul_f32 v[32:33], v[32:33], v[108:109] op_sel_hi:[1,0]
	v_pk_mul_f32 v[30:31], v[30:31], v[108:109] op_sel_hi:[1,0]
	v_pk_mul_f32 v[28:29], v[28:29], v[108:109] op_sel_hi:[1,0]
	v_pk_mul_f32 v[26:27], v[26:27], v[108:109] op_sel_hi:[1,0]
	v_pk_mul_f32 v[24:25], v[24:25], v[108:109] op_sel_hi:[1,0]
	v_pk_mul_f32 v[22:23], v[22:23], v[108:109] op_sel_hi:[1,0]
	v_pk_mul_f32 v[20:21], v[20:21], v[108:109] op_sel_hi:[1,0]
	v_pk_mul_f32 v[18:19], v[18:19], v[108:109] op_sel_hi:[1,0]
	v_pk_mul_f32 v[16:17], v[16:17], v[108:109] op_sel_hi:[1,0]
	v_pk_mul_f32 v[14:15], v[14:15], v[108:109] op_sel_hi:[1,0]
	v_pk_mul_f32 v[12:13], v[12:13], v[108:109] op_sel_hi:[1,0]
	v_pk_mul_f32 v[10:11], v[10:11], v[108:109] op_sel_hi:[1,0]
	v_pk_mul_f32 v[8:9], v[8:9], v[108:109] op_sel_hi:[1,0]
	v_pk_mul_f32 v[6:7], v[6:7], v[108:109] op_sel_hi:[1,0]
	v_pk_mul_f32 v[4:5], v[4:5], v[108:109] op_sel_hi:[1,0]
	v_pk_mul_f32 v[2:3], v[2:3], v[108:109] op_sel_hi:[1,0]
.LBB0_1173:
	v_max_f32_e32 v0, 0xefa18f08, v116
	v_cndmask_b32_e64 v117, v0, v198, s[2:3]
	v_sub_f32_e32 v0, v66, v117
	v_exp_f32_e32 v66, v0
	v_sub_f32_e32 v0, v82, v117
	v_exp_f32_e32 v82, v0
	v_sub_f32_e32 v0, v67, v117
	v_exp_f32_e32 v154, v0
	v_sub_f32_e32 v0, v83, v117
	v_exp_f32_e32 v0, v0
	v_sub_f32_e32 v67, v68, v117
	v_add_f32_e32 v155, v66, v82
	v_exp_f32_e32 v68, v67
	v_sub_f32_e32 v67, v84, v117
	v_pk_add_f32 v[110:111], v[154:155], v[0:1]
	v_exp_f32_e32 v84, v67
	v_sub_f32_e32 v67, v69, v117
	v_pk_add_f32 v[110:111], v[110:111], v[110:111] op_sel_hi:[0,1]
	v_exp_f32_e32 v156, v67
	v_sub_f32_e32 v67, v85, v117
	v_exp_f32_e32 v110, v67
	v_sub_f32_e32 v69, v70, v117
	v_add_f32_e32 v157, v68, v84
	v_exp_f32_e32 v70, v69
	v_sub_f32_e32 v69, v86, v117
	v_pk_add_f32 v[118:119], v[156:157], v[110:111]
	v_exp_f32_e32 v86, v69
	v_sub_f32_e32 v69, v71, v117
	v_pk_add_f32 v[158:159], v[118:119], v[118:119] op_sel_hi:[0,1]
	v_exp_f32_e32 v160, v69
	v_sub_f32_e32 v69, v87, v117
	v_exp_f32_e32 v158, v69
	v_sub_f32_e32 v69, v72, v117
	v_add_f32_e32 v161, v70, v86
	v_exp_f32_e32 v72, v69
	v_sub_f32_e32 v69, v88, v117
	v_pk_add_f32 v[126:127], v[160:161], v[158:159]
	v_exp_f32_e32 v88, v69
	v_sub_f32_e32 v69, v73, v117
	v_pk_add_f32 v[186:187], v[126:127], v[126:127] op_sel_hi:[0,1]
	v_exp_f32_e32 v188, v69
	v_sub_f32_e32 v69, v89, v117
	v_exp_f32_e32 v186, v69
	v_sub_f32_e32 v69, v74, v117
	v_add_f32_e32 v189, v72, v88
	v_exp_f32_e32 v74, v69
	v_sub_f32_e32 v69, v90, v117
	v_pk_add_f32 v[134:135], v[188:189], v[186:187]
	v_exp_f32_e32 v90, v69
	v_sub_f32_e32 v69, v75, v117
	v_pk_add_f32 v[190:191], v[134:135], v[134:135] op_sel_hi:[0,1]
	v_exp_f32_e32 v192, v69
	v_sub_f32_e32 v69, v91, v117
	v_exp_f32_e32 v190, v69
	v_sub_f32_e32 v69, v76, v117
	v_add_f32_e32 v193, v74, v90
	v_exp_f32_e32 v76, v69
	v_sub_f32_e32 v69, v92, v117
	v_pk_add_f32 v[142:143], v[192:193], v[190:191]
	v_exp_f32_e32 v92, v69
	v_sub_f32_e32 v69, v77, v117
	v_pk_add_f32 v[194:195], v[142:143], v[142:143] op_sel_hi:[0,1]
	v_exp_f32_e32 v224, v69
	v_sub_f32_e32 v69, v93, v117
	v_exp_f32_e32 v194, v69
	v_lshl_add_u32 v67, s46, 14, v112
	ds_read_b64_tr_b16 v[118:119], v67 offset:8192
	ds_read_b64_tr_b16 v[120:121], v67 offset:8704
	ds_read_b64_tr_b16 v[122:123], v67 offset:9216
	ds_read_b64_tr_b16 v[124:125], v67 offset:9728
	ds_read_b64_tr_b16 v[126:127], v67 offset:12288
	ds_read_b64_tr_b16 v[128:129], v67 offset:12800
	ds_read_b64_tr_b16 v[130:131], v67 offset:13312
	ds_read_b64_tr_b16 v[132:133], v67 offset:13824
	ds_read_b64_tr_b16 v[134:135], v67 offset:10240
	ds_read_b64_tr_b16 v[136:137], v67 offset:10752
	ds_read_b64_tr_b16 v[138:139], v67 offset:11264
	ds_read_b64_tr_b16 v[140:141], v67 offset:11776
	ds_read_b64_tr_b16 v[142:143], v67 offset:14336
	ds_read_b64_tr_b16 v[144:145], v67 offset:14848
	ds_read_b64_tr_b16 v[146:147], v67 offset:15360
	ds_read_b64_tr_b16 v[148:149], v67 offset:15872
	v_add_f32_e32 v225, v76, v92
	v_sub_f32_e32 v67, v78, v117
	v_pk_add_f32 v[150:151], v[224:225], v[194:195]
	v_exp_f32_e32 v78, v67
	v_sub_f32_e32 v67, v94, v117
	v_pk_add_f32 v[226:227], v[150:151], v[150:151] op_sel_hi:[0,1]
	v_cvt_pk_bf16_f32 v150, v66, v154
	v_cvt_pk_bf16_f32 v151, v68, v156
	v_cvt_pk_bf16_f32 v152, v70, v160
	v_cvt_pk_bf16_f32 v153, v72, v188
	v_exp_f32_e32 v94, v67
	v_sub_f32_e32 v67, v79, v117
	s_waitcnt lgkmcnt(0)
	v_mfma_f32_32x32x16_bf16 v[2:17], v[118:121], v[150:153], v[2:17]
	v_exp_f32_e32 v228, v67
	v_sub_f32_e32 v67, v95, v117
	v_exp_f32_e32 v226, v67
	v_sub_f32_e32 v67, v80, v117
	v_exp_f32_e32 v80, v67
	v_sub_f32_e32 v67, v81, v117
	v_exp_f32_e32 v81, v67
	v_mfma_f32_32x32x16_bf16 v[18:33], v[126:129], v[150:153], v[18:33]
	v_cvt_pk_bf16_f32 v118, v74, v192
	v_cvt_pk_bf16_f32 v119, v76, v224
	v_cvt_pk_bf16_f32 v120, v78, v228
	v_cvt_pk_bf16_f32 v121, v80, v81
	v_sub_f32_e32 v67, v96, v117
	v_exp_f32_e32 v96, v67
	v_sub_f32_e32 v67, v97, v117
	v_mfma_f32_32x32x16_bf16 v[2:17], v[122:125], v[118:121], v[2:17]
	v_exp_f32_e32 v97, v67
	v_add_f32_e32 v229, v78, v94
	v_pk_add_f32 v[122:123], v[228:229], v[226:227]
	v_add_f32_e32 v111, v80, v96
	v_pk_add_f32 v[122:123], v[122:123], v[122:123] op_sel_hi:[0,1]
	v_mov_b32_e32 v122, v97
	v_mfma_f32_32x32x16_bf16 v[18:33], v[130:133], v[118:121], v[18:33]
	v_cvt_pk_bf16_f32 v118, v82, v0
	v_cvt_pk_bf16_f32 v119, v84, v110
	v_cvt_pk_bf16_f32 v120, v86, v158
	v_cvt_pk_bf16_f32 v121, v88, v186
	v_mov_b32_e32 v110, v81
	v_pk_add_f32 v[110:111], v[110:111], v[122:123]
	v_mfma_f32_32x32x16_bf16 v[2:17], v[134:137], v[118:121], v[2:17]
	v_add_f32_e32 v0, v110, v111
	v_fma_f32 v115, v115, v108, v0
	v_mfma_f32_32x32x16_bf16 v[18:33], v[142:145], v[118:121], v[18:33]
	v_cvt_pk_bf16_f32 v118, v90, v190
	v_cvt_pk_bf16_f32 v119, v92, v194
	v_cvt_pk_bf16_f32 v120, v94, v226
	v_cvt_pk_bf16_f32 v121, v96, v97
	s_nop 1
	v_mfma_f32_32x32x16_bf16 v[2:17], v[138:141], v[118:121], v[2:17]
	v_mfma_f32_32x32x16_bf16 v[18:33], v[146:149], v[118:121], v[18:33]
	s_branch .LBB0_1175

.LBB0_1190:
	v_max_f32_e32 v107, 0xefa18f08, v108
	v_sub_f32_e32 v0, v34, v107
	v_exp_f32_e32 v34, v0
	v_sub_f32_e32 v0, v50, v107
	v_exp_f32_e32 v50, v0
	v_sub_f32_e32 v0, v35, v107
	v_exp_f32_e32 v110, v0
	v_sub_f32_e32 v0, v51, v107
	v_exp_f32_e32 v0, v0
	v_sub_f32_e32 v35, v36, v107
	v_add_f32_e32 v111, v34, v50
	v_exp_f32_e32 v36, v35
	v_sub_f32_e32 v35, v52, v107
	v_pk_add_f32 v[104:105], v[110:111], v[0:1]
	v_exp_f32_e32 v52, v35
	v_sub_f32_e32 v35, v37, v107
	v_pk_add_f32 v[104:105], v[104:105], v[104:105] op_sel_hi:[0,1]
	v_exp_f32_e32 v150, v35
	v_sub_f32_e32 v35, v53, v107
	v_exp_f32_e32 v104, v35
	v_sub_f32_e32 v37, v38, v107
	v_add_f32_e32 v151, v36, v52
	v_exp_f32_e32 v38, v37
	v_sub_f32_e32 v37, v54, v107
	v_pk_add_f32 v[114:115], v[150:151], v[104:105]
	v_exp_f32_e32 v54, v37
	v_sub_f32_e32 v37, v39, v107
	v_pk_add_f32 v[152:153], v[114:115], v[114:115] op_sel_hi:[0,1]
	v_exp_f32_e32 v154, v37
	v_sub_f32_e32 v37, v55, v107
	v_exp_f32_e32 v152, v37
	v_sub_f32_e32 v37, v40, v107
	v_add_f32_e32 v155, v38, v54
	v_exp_f32_e32 v40, v37
	v_sub_f32_e32 v37, v56, v107
	v_pk_add_f32 v[122:123], v[154:155], v[152:153]
	v_exp_f32_e32 v56, v37
	v_sub_f32_e32 v37, v41, v107
	v_pk_add_f32 v[156:157], v[122:123], v[122:123] op_sel_hi:[0,1]
	v_exp_f32_e32 v158, v37
	v_sub_f32_e32 v37, v57, v107
	v_exp_f32_e32 v156, v37
	v_sub_f32_e32 v37, v42, v107
	v_add_f32_e32 v159, v40, v56
	v_exp_f32_e32 v42, v37
	v_sub_f32_e32 v37, v58, v107
	v_pk_add_f32 v[130:131], v[158:159], v[156:157]
	v_exp_f32_e32 v58, v37
	v_sub_f32_e32 v37, v43, v107
	v_pk_add_f32 v[160:161], v[130:131], v[130:131] op_sel_hi:[0,1]
	v_exp_f32_e32 v186, v37
	v_sub_f32_e32 v37, v59, v107
	v_exp_f32_e32 v160, v37
	v_sub_f32_e32 v37, v44, v107
	v_add_f32_e32 v187, v42, v58
	v_exp_f32_e32 v44, v37
	v_sub_f32_e32 v37, v60, v107
	v_pk_add_f32 v[138:139], v[186:187], v[160:161]
	v_exp_f32_e32 v60, v37
	v_sub_f32_e32 v37, v45, v107
	v_pk_add_f32 v[188:189], v[138:139], v[138:139] op_sel_hi:[0,1]
	v_exp_f32_e32 v190, v37
	v_sub_f32_e32 v37, v61, v107
	v_exp_f32_e32 v188, v37
	v_lshl_add_u32 v35, s44, 14, v112
	ds_read_b64_tr_b16 v[114:115], v35 offset:8192
	ds_read_b64_tr_b16 v[116:117], v35 offset:8704
	ds_read_b64_tr_b16 v[118:119], v35 offset:9216
	ds_read_b64_tr_b16 v[120:121], v35 offset:9728
	ds_read_b64_tr_b16 v[122:123], v35 offset:12288
	ds_read_b64_tr_b16 v[124:125], v35 offset:12800
	ds_read_b64_tr_b16 v[126:127], v35 offset:13312
	ds_read_b64_tr_b16 v[128:129], v35 offset:13824
	ds_read_b64_tr_b16 v[130:131], v35 offset:10240
	ds_read_b64_tr_b16 v[132:133], v35 offset:10752
	ds_read_b64_tr_b16 v[134:135], v35 offset:11264
	ds_read_b64_tr_b16 v[136:137], v35 offset:11776
	ds_read_b64_tr_b16 v[138:139], v35 offset:14336
	ds_read_b64_tr_b16 v[140:141], v35 offset:14848
	ds_read_b64_tr_b16 v[142:143], v35 offset:15360
	ds_read_b64_tr_b16 v[144:145], v35 offset:15872
	v_add_f32_e32 v191, v44, v60
	v_sub_f32_e32 v35, v46, v107
	v_pk_add_f32 v[146:147], v[190:191], v[188:189]
	v_exp_f32_e32 v46, v35
	v_sub_f32_e32 v35, v62, v107
	v_pk_add_f32 v[192:193], v[146:147], v[146:147] op_sel_hi:[0,1]
	v_cvt_pk_bf16_f32 v146, v34, v110
	v_cvt_pk_bf16_f32 v147, v36, v150
	v_cvt_pk_bf16_f32 v148, v38, v154
	v_cvt_pk_bf16_f32 v149, v40, v158
	v_exp_f32_e32 v62, v35
	v_sub_f32_e32 v35, v47, v107
	s_waitcnt lgkmcnt(0)
	v_mfma_f32_32x32x16_bf16 v[18:33], v[114:117], v[146:149], v[18:33]
	v_exp_f32_e32 v194, v35
	v_sub_f32_e32 v35, v63, v107
	v_exp_f32_e32 v192, v35
	v_sub_f32_e32 v35, v48, v107
	v_exp_f32_e32 v48, v35
	v_sub_f32_e32 v35, v49, v107
	v_exp_f32_e32 v49, v35
	v_mfma_f32_32x32x16_bf16 v[2:17], v[122:125], v[146:149], v[2:17]
	v_cvt_pk_bf16_f32 v114, v42, v186
	v_cvt_pk_bf16_f32 v115, v44, v190
	v_cvt_pk_bf16_f32 v116, v46, v194
	v_cvt_pk_bf16_f32 v117, v48, v49
	v_sub_f32_e32 v35, v64, v107
	v_exp_f32_e32 v64, v35
	v_sub_f32_e32 v35, v65, v107
	v_mfma_f32_32x32x16_bf16 v[18:33], v[118:121], v[114:117], v[18:33]
	v_exp_f32_e32 v65, v35
	v_add_f32_e32 v195, v46, v62
	v_pk_add_f32 v[118:119], v[194:195], v[192:193]
	v_add_f32_e32 v105, v48, v64
	v_pk_add_f32 v[118:119], v[118:119], v[118:119] op_sel_hi:[0,1]
	v_mov_b32_e32 v118, v65
	v_mfma_f32_32x32x16_bf16 v[2:17], v[126:129], v[114:117], v[2:17]
	v_cvt_pk_bf16_f32 v114, v50, v0
	v_cvt_pk_bf16_f32 v115, v52, v104
	v_cvt_pk_bf16_f32 v116, v54, v152
	v_cvt_pk_bf16_f32 v117, v56, v156
	v_mov_b32_e32 v104, v49
	v_pk_add_f32 v[104:105], v[104:105], v[118:119]
	v_mfma_f32_32x32x16_bf16 v[18:33], v[130:133], v[114:117], v[18:33]
	v_add_f32_e32 v0, v104, v105
	v_fma_f32 v106, v106, v102, v0
	v_mfma_f32_32x32x16_bf16 v[2:17], v[138:141], v[114:117], v[2:17]
	v_cvt_pk_bf16_f32 v114, v58, v160
	v_cvt_pk_bf16_f32 v115, v60, v188
	v_cvt_pk_bf16_f32 v116, v62, v192
	v_cvt_pk_bf16_f32 v117, v64, v65
	s_nop 1
	v_mfma_f32_32x32x16_bf16 v[18:33], v[134:137], v[114:117], v[18:33]
	v_mfma_f32_32x32x16_bf16 v[2:17], v[142:145], v[114:117], v[2:17]
	s_branch .LBB0_1192

.LBB0_1201:
	v_max_f32_e32 v108, 0xefa18f08, v107
	v_sub_f32_e32 v0, v66, v108
	v_exp_f32_e32 v66, v0
	v_sub_f32_e32 v0, v82, v108
	v_exp_f32_e32 v82, v0
	v_sub_f32_e32 v0, v67, v108
	v_exp_f32_e32 v110, v0
	v_sub_f32_e32 v0, v83, v108
	v_exp_f32_e32 v0, v0
	v_sub_f32_e32 v67, v68, v108
	v_add_f32_e32 v111, v66, v82
	v_exp_f32_e32 v68, v67
	v_sub_f32_e32 v67, v84, v108
	v_pk_add_f32 v[104:105], v[110:111], v[0:1]
	v_exp_f32_e32 v84, v67
	v_sub_f32_e32 v67, v69, v108
	v_pk_add_f32 v[104:105], v[104:105], v[104:105] op_sel_hi:[0,1]
	v_exp_f32_e32 v150, v67
	v_sub_f32_e32 v67, v85, v108
	v_exp_f32_e32 v104, v67
	v_sub_f32_e32 v69, v70, v108
	v_add_f32_e32 v151, v68, v84
	v_exp_f32_e32 v70, v69
	v_sub_f32_e32 v69, v86, v108
	v_pk_add_f32 v[114:115], v[150:151], v[104:105]
	v_exp_f32_e32 v86, v69
	v_sub_f32_e32 v69, v71, v108
	v_pk_add_f32 v[152:153], v[114:115], v[114:115] op_sel_hi:[0,1]
	v_exp_f32_e32 v154, v69
	v_sub_f32_e32 v69, v87, v108
	v_exp_f32_e32 v152, v69
	v_sub_f32_e32 v69, v72, v108
	v_add_f32_e32 v155, v70, v86
	v_exp_f32_e32 v72, v69
	v_sub_f32_e32 v69, v88, v108
	v_pk_add_f32 v[122:123], v[154:155], v[152:153]
	v_exp_f32_e32 v88, v69
	v_sub_f32_e32 v69, v73, v108
	v_pk_add_f32 v[156:157], v[122:123], v[122:123] op_sel_hi:[0,1]
	v_exp_f32_e32 v158, v69
	v_sub_f32_e32 v69, v89, v108
	v_exp_f32_e32 v156, v69
	v_sub_f32_e32 v69, v74, v108
	v_add_f32_e32 v159, v72, v88
	v_exp_f32_e32 v74, v69
	v_sub_f32_e32 v69, v90, v108
	v_pk_add_f32 v[130:131], v[158:159], v[156:157]
	v_exp_f32_e32 v90, v69
	v_sub_f32_e32 v69, v75, v108
	v_pk_add_f32 v[160:161], v[130:131], v[130:131] op_sel_hi:[0,1]
	v_exp_f32_e32 v186, v69
	v_sub_f32_e32 v69, v91, v108
	v_exp_f32_e32 v160, v69
	v_sub_f32_e32 v69, v76, v108
	v_add_f32_e32 v187, v74, v90
	v_exp_f32_e32 v76, v69
	v_sub_f32_e32 v69, v92, v108
	v_pk_add_f32 v[138:139], v[186:187], v[160:161]
	v_exp_f32_e32 v92, v69
	v_sub_f32_e32 v69, v77, v108
	v_pk_add_f32 v[188:189], v[138:139], v[138:139] op_sel_hi:[0,1]
	v_exp_f32_e32 v190, v69
	v_sub_f32_e32 v69, v93, v108
	v_exp_f32_e32 v188, v69
	v_lshl_add_u32 v67, s45, 14, v112
	ds_read_b64_tr_b16 v[114:115], v67 offset:8192
	ds_read_b64_tr_b16 v[116:117], v67 offset:8704
	ds_read_b64_tr_b16 v[118:119], v67 offset:9216
	ds_read_b64_tr_b16 v[120:121], v67 offset:9728
	ds_read_b64_tr_b16 v[122:123], v67 offset:12288
	ds_read_b64_tr_b16 v[124:125], v67 offset:12800
	ds_read_b64_tr_b16 v[126:127], v67 offset:13312
	ds_read_b64_tr_b16 v[128:129], v67 offset:13824
	ds_read_b64_tr_b16 v[130:131], v67 offset:10240
	ds_read_b64_tr_b16 v[132:133], v67 offset:10752
	ds_read_b64_tr_b16 v[134:135], v67 offset:11264
	ds_read_b64_tr_b16 v[136:137], v67 offset:11776
	ds_read_b64_tr_b16 v[138:139], v67 offset:14336
	ds_read_b64_tr_b16 v[140:141], v67 offset:14848
	ds_read_b64_tr_b16 v[142:143], v67 offset:15360
	ds_read_b64_tr_b16 v[144:145], v67 offset:15872
	v_add_f32_e32 v191, v76, v92
	v_sub_f32_e32 v67, v78, v108
	v_pk_add_f32 v[146:147], v[190:191], v[188:189]
	v_exp_f32_e32 v78, v67
	v_sub_f32_e32 v67, v94, v108
	v_pk_add_f32 v[192:193], v[146:147], v[146:147] op_sel_hi:[0,1]
	v_cvt_pk_bf16_f32 v146, v66, v110
	v_cvt_pk_bf16_f32 v147, v68, v150
	v_cvt_pk_bf16_f32 v148, v70, v154
	v_cvt_pk_bf16_f32 v149, v72, v158
	v_exp_f32_e32 v94, v67
	v_sub_f32_e32 v67, v79, v108
	s_waitcnt lgkmcnt(0)
	v_mfma_f32_32x32x16_bf16 v[18:33], v[114:117], v[146:149], v[18:33]
	v_exp_f32_e32 v194, v67
	v_sub_f32_e32 v67, v95, v108
	v_exp_f32_e32 v192, v67
	v_sub_f32_e32 v67, v80, v108
	v_exp_f32_e32 v80, v67
	v_sub_f32_e32 v67, v81, v108
	v_exp_f32_e32 v81, v67
	v_mfma_f32_32x32x16_bf16 v[2:17], v[122:125], v[146:149], v[2:17]
	v_cvt_pk_bf16_f32 v114, v74, v186
	v_cvt_pk_bf16_f32 v115, v76, v190
	v_cvt_pk_bf16_f32 v116, v78, v194
	v_cvt_pk_bf16_f32 v117, v80, v81
	v_sub_f32_e32 v67, v96, v108
	v_exp_f32_e32 v96, v67
	v_sub_f32_e32 v67, v97, v108
	v_mfma_f32_32x32x16_bf16 v[18:33], v[118:121], v[114:117], v[18:33]
	v_exp_f32_e32 v97, v67
	v_add_f32_e32 v195, v78, v94
	v_pk_add_f32 v[118:119], v[194:195], v[192:193]
	v_add_f32_e32 v105, v80, v96
	v_pk_add_f32 v[118:119], v[118:119], v[118:119] op_sel_hi:[0,1]
	v_mov_b32_e32 v118, v97
	v_mfma_f32_32x32x16_bf16 v[2:17], v[126:129], v[114:117], v[2:17]
	v_cvt_pk_bf16_f32 v114, v82, v0
	v_cvt_pk_bf16_f32 v115, v84, v104
	v_cvt_pk_bf16_f32 v116, v86, v152
	v_cvt_pk_bf16_f32 v117, v88, v156
	v_mov_b32_e32 v104, v81
	v_pk_add_f32 v[104:105], v[104:105], v[118:119]
	v_mfma_f32_32x32x16_bf16 v[18:33], v[130:133], v[114:117], v[18:33]
	v_add_f32_e32 v0, v104, v105
	s_add_i32 s0, s43, 1
	v_fma_f32 v106, v106, v102, v0
	s_cmp_lg_u32 s43, 5
	v_mfma_f32_32x32x16_bf16 v[2:17], v[138:141], v[114:117], v[2:17]
	v_cvt_pk_bf16_f32 v114, v90, v160
	v_cvt_pk_bf16_f32 v115, v92, v188
	v_cvt_pk_bf16_f32 v116, v94, v192
	v_cvt_pk_bf16_f32 v117, v96, v97
	s_nop 1
	v_mfma_f32_32x32x16_bf16 v[18:33], v[134:137], v[114:117], v[18:33]
	s_cselect_b32 s43, s0, 0
	v_mfma_f32_32x32x16_bf16 v[2:17], v[142:145], v[114:117], v[2:17]
	s_branch .LBB0_1180
